# P2: conv/gate merge fused into each prompt attention chunk (applied in registers before the single MIX store; SGA/BG/U loads issued early in the chunk); separate merge pass, its barrier and fence remo
# speedup vs baseline: 1.0071x; 1.0071x over previous
.LBB0_706:
	s_or_b64 exec, exec, s[4:5]
	v_readlane_b32 s19, v254, 0
	s_lshl_b32 s33, s19, 1
	s_cmpk_lt_i32 s19, 0x100
	s_cselect_b64 s[2:3], -1, 0
	v_bfe_u32 v125, v171, 3, 2
	v_writelane_b32 v255, s2, 0
	s_cmpk_gt_i32 s19, 0xff
	v_cmp_eq_u32_e64 s[88:89], 0, v170
	v_writelane_b32 v255, s3, 1
	v_or_b32_e32 v124, 32, v170
	v_and_b32_e32 v156, 7, v171
	v_cmp_gt_u32_e64 s[4:5], 32, v170
	v_lshlrev_b32_e32 v128, 11, v125
	v_and_b32_e32 v126, 32, v170
	s_waitcnt lgkmcnt(0)
	s_barrier
	s_cbranch_scc1 .LBB0_874
	v_lshlrev_b32_e32 v0, 3, v171
	v_and_b32_e32 v1, 56, v0
	v_readlane_b32 s2, v254, 56
	v_lshlrev_b32_e32 v130, 1, v1
	v_mov_b32_e32 v131, 0
	v_readlane_b32 s3, v254, 57
	v_lshrrev_b32_e32 v3, 5, v170
	v_lshlrev_b32_e32 v137, 2, v3
	v_lshl_add_u64 v[132:133], s[2:3], 0, v[130:131]
	v_readlane_b32 s2, v254, 58
	v_readlane_b32 s3, v254, 59
	v_and_b32_e32 v136, 31, v171
	v_lshlrev_b32_e32 v138, 3, v3
	v_lshl_add_u32 v129, v3, 4, 0
	v_or_b32_e32 v3, 27, v137
	v_lshl_add_u64 v[134:135], s[2:3], 0, v[130:131]
	v_cmp_gt_u32_e64 s[2:3], v3, v136
	v_or_b32_e32 v3, 2, v137
	v_or_b32_e32 v4, 3, v137
	v_writelane_b32 v255, s2, 2
	v_or_b32_e32 v5, 8, v137
	v_readlane_b32 s56, v254, 6
	v_writelane_b32 v255, s3, 3
	v_cmp_gt_u32_e64 s[2:3], v137, v136
	v_mov_b32_e32 v127, v131
	v_readlane_b32 s57, v254, 7
	v_writelane_b32 v255, s2, 4
	v_readlane_b32 s58, v254, 8
	v_readlane_b32 s59, v254, 9
	v_writelane_b32 v255, s3, 5
	v_cmp_ge_u32_e64 s[2:3], v137, v136
	v_readlane_b32 s60, v254, 10
	v_readlane_b32 s61, v254, 11
	v_writelane_b32 v255, s2, 6
	v_readlane_b32 s62, v254, 12
	v_readlane_b32 s63, v254, 13
	v_writelane_b32 v255, s3, 7
	v_cmp_gt_u32_e64 s[2:3], v3, v136
	v_readlane_b32 s64, v254, 14
	v_readlane_b32 s65, v254, 15
	v_writelane_b32 v255, s2, 8
	v_readlane_b32 s66, v254, 16
	v_readlane_b32 s67, v254, 17
	v_writelane_b32 v255, s3, 9
	v_cmp_gt_u32_e64 s[2:3], v4, v136
	v_readlane_b32 s68, v254, 18
	v_readlane_b32 s69, v254, 19
	v_writelane_b32 v255, s2, 10
	v_readlane_b32 s70, v254, 20
	v_readlane_b32 s71, v254, 21
	v_writelane_b32 v255, s3, 11
	v_cmp_gt_u32_e64 s[2:3], v5, v136
	v_or_b32_e32 v5, 9, v137
	v_lshl_add_u64 v[140:141], s[60:61], 0, v[126:127]
	v_writelane_b32 v255, s2, 12
	v_readlane_b32 s56, v254, 22
	v_readlane_b32 s60, v254, 26
	v_writelane_b32 v255, s3, 13
	v_cmp_gt_u32_e64 s[2:3], v5, v136
	v_or_b32_e32 v5, 10, v137
	v_readlane_b32 s61, v254, 27
	v_writelane_b32 v255, s2, 14
	v_cmp_eq_u32_e64 s[50:51], v4, v125
	v_add_u32_e32 v4, 0x200, v171
	v_writelane_b32 v255, s3, 15
	v_cmp_gt_u32_e64 s[2:3], v5, v136
	v_or_b32_e32 v5, 11, v137
	v_add_u32_e32 v7, 0x600, v171
	v_writelane_b32 v255, s2, 16
	v_lshrrev_b32_e32 v161, 3, v4
	v_or_b32_e32 v162, 0x80, v177
	v_writelane_b32 v255, s3, 17
	v_cmp_gt_u32_e64 s[2:3], v5, v136
	v_or_b32_e32 v5, 16, v137
	v_lshrrev_b32_e32 v163, 3, v7
	v_writelane_b32 v255, s2, 18
	v_add_u32_e32 v2, 0, v130
	v_cmp_gt_u32_e64 s[48:49], v3, v125
	v_writelane_b32 v255, s3, 19
	v_cmp_gt_u32_e64 s[2:3], v5, v136
	v_or_b32_e32 v5, 17, v137
	v_and_b32_e32 v160, 0x1f8, v0
	v_writelane_b32 v255, s2, 20
	v_mul_u32_u24_e32 v0, 0x90, v177
	v_lshl_add_u32 v3, v177, 1, 0
	v_writelane_b32 v255, s3, 21
	v_cmp_gt_u32_e64 s[2:3], v5, v136
	v_or_b32_e32 v5, 18, v137
	v_mul_u32_u24_e32 v1, 0x208, v1
	v_writelane_b32 v255, s2, 22
	v_mul_u32_u24_e32 v4, 0x90, v161
	v_mul_u32_u24_e32 v6, 0x90, v162
	v_writelane_b32 v255, s3, 23
	v_cmp_gt_u32_e64 s[2:3], v5, v136
	v_or_b32_e32 v5, 19, v137
	v_mul_u32_u24_e32 v7, 0x90, v163
	v_writelane_b32 v255, s2, 24
	v_lshl_add_u32 v8, v163, 1, 0
	s_mov_b32 s92, 0
	v_writelane_b32 v255, s3, 25
	v_cmp_gt_u32_e64 s[2:3], v5, v136
	v_or_b32_e32 v5, 24, v137
	v_sub_u32_e32 v139, v129, v138
	v_writelane_b32 v255, s2, 26
	v_mul_u32_u24_e32 v157, 0x208, v136
	v_mul_u32_u24_e32 v158, 0x208, v124
	v_writelane_b32 v255, s3, 27
	v_cmp_gt_u32_e64 s[2:3], v5, v136
	v_or_b32_e32 v5, 25, v137
	v_cmp_gt_u32_e64 s[42:43], 4, v136
	v_writelane_b32 v255, s2, 28
	v_cmp_gt_u32_e64 s[44:45], v137, v125
	v_cmp_lt_u32_e64 s[46:47], v137, v125
	v_writelane_b32 v255, s3, 29
	v_cmp_gt_u32_e64 s[2:3], v5, v136
	v_or_b32_e32 v5, 26, v137
	v_cmp_lt_u32_e64 s[52:53], 7, v136
	v_writelane_b32 v255, s2, 30
	v_cmp_gt_u32_e64 s[54:55], 16, v136
	v_lshrrev_b32_e32 v159, 6, v171
	v_writelane_b32 v255, s3, 31
	v_cmp_gt_u32_e64 s[2:3], v5, v136
	v_lshl_add_u32 v5, v161, 1, 0
	s_movk_i32 s16, 0x90
	v_writelane_b32 v255, s2, 32
	v_add_u32_e32 v127, v2, v0
	v_add_u32_e32 v164, v2, v4
	v_writelane_b32 v255, s3, 33
	v_cmp_lt_u32_e64 s[2:3], v137, v136
	v_add_u32_e32 v165, v5, v1
	v_add_u32_e32 v166, v2, v6
	v_writelane_b32 v255, s2, 34
	v_add_u32_e32 v167, v2, v7
	v_add_u32_e32 v173, v8, v1
	v_writelane_b32 v255, s3, 35
	s_lshl_b32 s2, s76, 1
	s_add_u32 s10, s60, 0x2000
	s_addc_u32 s11, s61, 0
	s_add_u32 s6, s60, 0x4000
	v_writelane_b32 v255, s2, 36
	s_addc_u32 s7, s61, 0
	s_add_i32 s2, 0, 0x1d4c0
	v_writelane_b32 v255, s2, 37
	s_mov_b32 s17, 0xf149f2ca
	s_mov_b32 s18, 0x3e38aa3b
	v_lshlrev_b32_e32 v142, 2, v128
	v_add_u32_e32 v175, v3, v1
	v_mov_b32_e32 v179, 0xf149f2ca
	v_mov_b32_e32 v180, 0x3e38aa3b
	v_readlane_b32 s57, v254, 23
	v_readlane_b32 s58, v254, 24
	v_readlane_b32 s59, v254, 25
	v_readlane_b32 s62, v254, 28
	v_readlane_b32 s63, v254, 29
	v_readlane_b32 s64, v254, 30
	v_readlane_b32 s65, v254, 31
	v_readlane_b32 s66, v254, 32
	v_readlane_b32 s67, v254, 33
	v_readlane_b32 s68, v254, 34
	v_readlane_b32 s69, v254, 35
	v_readlane_b32 s70, v254, 36
	v_readlane_b32 s71, v254, 37
	s_branch .LBB0_709



.LBB0_728:
	s_or_b64 exec, exec, s[12:13]
	v_readfirstlane_b32 s14, v0
	s_cmp_ge_i32 s14, s22
	s_mov_b64 s[12:13], -1
	s_cbranch_scc1 .LBB0_723
	s_cmp_ge_i32 s14, s21
	v_lshlrev_b32_e32 v92, 1, v138
	v_mbcnt_hi_u32_b32 v102, -1, v220
	s_cbranch_scc0 .LBB0_731
	s_sub_i32 s12, s14, s21
	s_and_b32 s15, s12, 3
	s_lshl_b32 s13, s15, 5
	v_or_b32_e32 v0, s13, v154
	s_lshr_b32 s12, s12, 2
	v_ashrrev_i32_e32 v1, 31, v0
	v_readlane_b32 s24, v254, 54
	v_lshlrev_b64 v[84:85], 12, v[0:1]
	v_readlane_b32 s25, v254, 55
	s_add_i32 s12, s12, s23
	v_mov_b32_e32 v93, v131
	v_lshl_add_u64 v[0:1], s[24:25], 0, v[84:85]
	s_lshl_b32 s24, s12, 7
	s_mov_b32 s25, s92
	v_lshl_add_u64 v[0:1], v[0:1], 0, s[24:25]
	v_lshl_add_u64 v[90:91], v[0:1], 0, v[92:93]
	global_load_dwordx4 v[68:71], v[90:91], off
	global_load_dwordx4 v[64:67], v[90:91], off offset:32
	s_add_i32 s93, s15, 1
	v_lshl_or_b32 v4, s93, 5, v136
	v_mad_u32_u24 v94, v4, s16, v129
	ds_read_b128 v[16:19], v94
	ds_read_b128 v[76:79], v94 offset:32
	s_add_i32 s94, s15, 2
	v_lshl_or_b32 v20, s94, 5, v136
	v_mad_u32_u24 v95, v20, s16, v129
	v_or_b32_e32 v2, s13, v136
	s_add_i32 s95, s15, 3
	v_mad_u32_u24 v93, v2, s16, v129
	v_lshl_or_b32 v20, s95, 5, v136
	ds_read_b128 v[0:3], v93
	ds_read_b128 v[72:75], v93 offset:32
	v_mad_u32_u24 v96, v20, s16, v129
	s_mov_b32 s13, s92
	v_readlane_b32 s56, v254, 22
	s_or_b32 s24, s15, 4
	s_lshl_b64 vcc, s[12:13], 2
	v_readlane_b32 s58, v254, 24
	v_readlane_b32 s59, v254, 25
	s_add_u32 vcc_lo, s58, vcc_lo
	s_addc_u32 vcc_hi, s59, vcc_hi
	s_cmp_eq_u32 s15, 3
	v_readlane_b32 s57, v254, 23
	v_readlane_b32 s56, v255, 4
	v_readlane_b32 s57, v255, 5
	v_readlane_b32 s60, v254, 26
	v_readlane_b32 s61, v254, 27
	v_readlane_b32 s62, v254, 28
	v_readlane_b32 s63, v254, 29
	v_readlane_b32 s64, v254, 30
	v_readlane_b32 s65, v254, 31
	v_readlane_b32 s66, v254, 32
	v_readlane_b32 s67, v254, 33
	v_readlane_b32 s68, v254, 34
	v_readlane_b32 s69, v254, 35
	v_readlane_b32 s70, v254, 36
	v_readlane_b32 s71, v254, 37
	s_waitcnt vmcnt(1) lgkmcnt(3)
	v_mfma_f32_32x32x16_bf16 v[48:63], v[16:19], v[68:71], 0
	ds_read_b128 v[16:19], v95
	ds_read_b128 v[80:83], v95 offset:32
	s_waitcnt lgkmcnt(1)
	v_mfma_f32_32x32x16_bf16 v[32:47], v[16:19], v[68:71], 0
	ds_read_b128 v[16:19], v96
	ds_read_b128 v[86:89], v96 offset:32
	s_waitcnt vmcnt(0)
	v_mfma_f32_32x32x16_bf16 v[48:63], v[76:79], v[64:67], v[48:63]
	global_load_dwordx4 v[76:79], v[90:91], off offset:64
	v_mfma_f32_32x32x16_bf16 v[0:15], v[0:3], v[68:71], 0
	v_mfma_f32_32x32x16_bf16 v[0:15], v[72:75], v[64:67], v[0:15]
	global_load_dwordx4 v[72:75], v[90:91], off offset:96
	s_waitcnt lgkmcnt(1)
	v_mfma_f32_32x32x16_bf16 v[16:31], v[16:19], v[68:71], 0
	v_mfma_f32_32x32x16_bf16 v[32:47], v[80:83], v[64:67], v[32:47]
	s_waitcnt lgkmcnt(0)
	v_mfma_f32_32x32x16_bf16 v[16:31], v[86:89], v[64:67], v[16:31]
	ds_read_b128 v[86:89], v93 offset:64
	ds_read_b128 v[80:83], v93 offset:96
	s_waitcnt vmcnt(1) lgkmcnt(1)
	v_mfma_f32_32x32x16_bf16 v[0:15], v[86:89], v[76:79], v[0:15]
	ds_read_b128 v[86:89], v94 offset:64
	ds_read_b128 v[98:101], v94 offset:96
	s_waitcnt lgkmcnt(1)
	v_mfma_f32_32x32x16_bf16 v[48:63], v[86:89], v[76:79], v[48:63]
	ds_read_b128 v[86:89], v95 offset:64
	ds_read_b128 v[104:107], v95 offset:96
	s_waitcnt lgkmcnt(1)
	v_mfma_f32_32x32x16_bf16 v[32:47], v[86:89], v[76:79], v[32:47]
	ds_read_b128 v[86:89], v96 offset:64
	ds_read_b128 v[112:115], v96 offset:96
	global_load_dword v96, v131, vcc
	s_mov_b32 s62, 0x6e80000
	s_mov_b32 s63, 0
	s_mov_b32 s64, 0x4c80000
	s_mov_b32 s65, 0
	s_mov_b32 s66, 0x2a80000
	s_mov_b32 s67, 0
	v_lshl_add_u64 v[190:191], v[90:91], 0, s[62:63]
	global_load_dwordx4 v[222:225], v[190:191], off
	global_load_dwordx4 v[226:229], v[190:191], off offset:32
	global_load_dwordx4 v[230:233], v[190:191], off offset:64
	global_load_dwordx4 v[234:237], v[190:191], off offset:96
	v_lshl_add_u64 v[190:191], v[90:91], 0, s[64:65]
	global_load_dwordx4 v[238:241], v[190:191], off
	global_load_dwordx4 v[242:245], v[190:191], off offset:32
	global_load_dwordx4 v[246:249], v[190:191], off offset:64
	global_load_dwordx4 v[250:253], v[190:191], off offset:96
	v_lshl_add_u64 v[190:191], v[90:91], 0, s[66:67]
	global_load_dwordx4 v[182:185], v[190:191], off
	global_load_dwordx4 v[186:189], v[190:191], off offset:32
	global_load_dwordx4 v[202:205], v[190:191], off offset:64
	global_load_dwordx4 v[206:209], v[190:191], off offset:96
	s_cselect_b64 vcc, -1, 0
	s_or_b64 vcc, s[8:9], vcc
	s_xor_b32 s13, s15, 2
	s_cmp_lt_u32 s13, 2
	s_waitcnt lgkmcnt(1)
	v_mfma_f32_32x32x16_bf16 v[16:31], v[86:89], v[76:79], v[16:31]
	s_waitcnt vmcnt(13)
	v_mfma_f32_32x32x16_bf16 v[48:63], v[98:101], v[72:75], v[48:63]
	v_mfma_f32_32x32x16_bf16 v[32:47], v[104:107], v[72:75], v[32:47]
	s_nop 10
	v_cndmask_b32_e32 v48, v179, v48, vcc
	v_cndmask_b32_e32 v49, v179, v49, vcc
	v_cndmask_b32_e32 v50, v179, v50, vcc
	v_cndmask_b32_e32 v51, v179, v51, vcc
	v_cndmask_b32_e32 v52, v179, v52, vcc
	v_cndmask_b32_e32 v53, v179, v53, vcc
	v_cndmask_b32_e32 v54, v179, v54, vcc
	s_waitcnt lgkmcnt(0)
	v_mfma_f32_32x32x16_bf16 v[16:31], v[112:115], v[72:75], v[16:31]
	v_cndmask_b32_e32 v55, v179, v55, vcc
	v_cndmask_b32_e32 v56, v179, v56, vcc
	v_cndmask_b32_e32 v57, v179, v57, vcc
	v_cndmask_b32_e32 v58, v179, v58, vcc
	v_cndmask_b32_e32 v59, v179, v59, vcc
	v_cndmask_b32_e32 v60, v179, v60, vcc
	v_cndmask_b32_e32 v61, v179, v61, vcc
	v_cndmask_b32_e32 v62, v179, v62, vcc
	v_cndmask_b32_e32 v116, v179, v63, vcc
	s_cselect_b64 vcc, -1, 0
	s_or_b64 vcc, s[8:9], vcc
	s_or_b32 s13, s15, s20
	s_cmp_eq_u32 s13, 0
	v_cndmask_b32_e32 v117, v179, v32, vcc
	v_cndmask_b32_e32 v118, v179, v33, vcc
	v_cndmask_b32_e32 v119, v179, v34, vcc
	v_cndmask_b32_e32 v120, v179, v35, vcc
	v_cndmask_b32_e32 v121, v179, v36, vcc
	v_cndmask_b32_e32 v122, v179, v37, vcc
	v_cndmask_b32_e32 v123, v179, v38, vcc
	v_cndmask_b32_e32 v130, v179, v39, vcc
	v_cndmask_b32_e32 v63, v179, v40, vcc
	v_cndmask_b32_e32 v111, v179, v41, vcc
	v_cndmask_b32_e32 v110, v179, v42, vcc
	v_cndmask_b32_e32 v109, v179, v43, vcc
	v_cndmask_b32_e32 v108, v179, v44, vcc
	v_cndmask_b32_e32 v107, v179, v45, vcc
	v_cndmask_b32_e32 v106, v179, v46, vcc
	v_cndmask_b32_e32 v105, v179, v47, vcc
	s_cselect_b64 vcc, -1, 0
	v_cndmask_b32_e32 v103, v17, v179, vcc
	v_and_b32_e32 v17, 64, v102
	v_cndmask_b32_e32 v104, v16, v179, vcc
	v_xor_b32_e32 v16, 32, v102
	v_add_u32_e32 v17, 64, v17
	v_cndmask_b32_e32 v101, v18, v179, vcc
	v_cndmask_b32_e32 v100, v19, v179, vcc
	v_cndmask_b32_e32 v99, v20, v179, vcc
	v_cndmask_b32_e32 v98, v21, v179, vcc
	v_cndmask_b32_e32 v97, v22, v179, vcc
	v_cndmask_b32_e32 v95, v23, v179, vcc
	v_cndmask_b32_e32 v94, v24, v179, vcc
	v_cndmask_b32_e32 v93, v25, v179, vcc
	v_cndmask_b32_e32 v91, v26, v179, vcc
	v_cndmask_b32_e32 v90, v27, v179, vcc
	v_cndmask_b32_e32 v86, v28, v179, vcc
	v_cndmask_b32_e32 v87, v29, v179, vcc
	v_cndmask_b32_e32 v88, v30, v179, vcc
	v_cndmask_b32_e32 v89, v31, v179, vcc
	v_cmp_lt_i32_e32 vcc, v16, v17
	v_mfma_f32_32x32x16_bf16 v[0:15], v[80:83], v[72:75], v[0:15]
	s_mov_b32 s13, 0x3fb8aa3b
	v_cndmask_b32_e32 v44, v102, v16, vcc
	v_lshl_or_b32 v16, s24, 5, v136
	v_mad_u32_u24 v40, v16, s16, v129
	ds_read_b128 v[16:19], v40
	ds_read_b128 v[32:35], v40 offset:32
	ds_read_b128 v[36:39], v40 offset:64
	ds_read_b128 v[40:43], v40 offset:96
	v_lshlrev_b32_e32 v112, 2, v44
	s_waitcnt lgkmcnt(3)
	v_mfma_f32_32x32x16_bf16 v[16:31], v[16:19], v[68:71], 0
	s_nop 0
	v_cndmask_b32_e64 v0, v179, v0, s[26:27]
	v_cndmask_b32_e64 v1, v179, v1, s[28:29]
	v_max3_f32 v45, v0, s17, v1
	v_cndmask_b32_e64 v2, v179, v2, s[30:31]
	v_cndmask_b32_e64 v3, v179, v3, s[34:35]
	v_cndmask_b32_e64 v4, v179, v4, s[36:37]
	v_cndmask_b32_e64 v5, v179, v5, s[38:39]
	s_waitcnt lgkmcnt(2)
	v_mfma_f32_32x32x16_bf16 v[16:31], v[32:35], v[64:67], v[16:31]
	v_max3_f32 v32, v45, v2, v3
	v_max3_f32 v32, v32, v4, v5
	v_cndmask_b32_e64 v6, v179, v6, s[96:97]
	v_cndmask_b32_e64 v7, v179, v7, s[2:3]
	v_max3_f32 v32, v32, v6, v7
	v_cndmask_b32_e64 v8, v179, v8, s[72:73]
	v_cndmask_b32_e64 v9, v179, v9, s[74:75]
	s_waitcnt lgkmcnt(1)
	v_mfma_f32_32x32x16_bf16 v[16:31], v[36:39], v[76:79], v[16:31]
	v_max3_f32 v32, v32, v8, v9
	v_cndmask_b32_e64 v34, v179, v10, s[76:77]
	v_cndmask_b32_e64 v11, v179, v11, s[78:79]
	v_max3_f32 v10, v32, v34, v11
	v_cndmask_b32_e64 v12, v179, v12, s[80:81]
	v_cndmask_b32_e64 v13, v179, v13, s[82:83]
	v_max3_f32 v10, v10, v12, v13
	s_waitcnt lgkmcnt(0)
	v_mfma_f32_32x32x16_bf16 v[16:31], v[40:43], v[72:75], v[16:31]
	v_cndmask_b32_e64 v14, v179, v14, s[84:85]
	v_cndmask_b32_e64 v15, v179, v15, s[86:87]
	v_max3_f32 v10, v10, v14, v15
	v_max3_f32 v10, v10, v48, v49
	v_max3_f32 v10, v10, v50, v51
	v_max3_f32 v10, v10, v52, v53
	v_max3_f32 v10, v10, v54, v55
	s_nop 4
	v_cndmask_b32_e64 v16, v16, v179, s[56:57]
	v_readlane_b32 s56, v255, 34
	v_readlane_b32 s57, v255, 35
	v_max3_f32 v10, v10, v56, v57
	v_max3_f32 v10, v10, v58, v59
	v_cndmask_b32_e64 v17, v179, v17, s[56:57]
	v_readlane_b32 s56, v255, 8
	v_readlane_b32 s57, v255, 9
	v_max3_f32 v10, v10, v60, v61
	v_max3_f32 v10, v10, v62, v116
	v_cndmask_b32_e64 v18, v18, v179, s[56:57]
	v_readlane_b32 s56, v255, 10
	v_readlane_b32 s57, v255, 11
	v_max3_f32 v10, v10, v117, v118
	v_max3_f32 v10, v10, v119, v120
	v_cndmask_b32_e64 v19, v19, v179, s[56:57]
	v_readlane_b32 s56, v255, 12
	v_readlane_b32 s57, v255, 13
	v_max3_f32 v10, v10, v121, v122
	v_max3_f32 v10, v10, v123, v130
	v_cndmask_b32_e64 v20, v20, v179, s[56:57]
	v_readlane_b32 s56, v255, 14
	v_readlane_b32 s57, v255, 15
	v_max3_f32 v10, v10, v63, v111
	v_max3_f32 v10, v10, v110, v109
	v_cndmask_b32_e64 v21, v21, v179, s[56:57]
	v_readlane_b32 s56, v255, 16
	v_readlane_b32 s57, v255, 17
	v_max3_f32 v10, v10, v108, v107
	v_max3_f32 v10, v10, v106, v105
	v_cndmask_b32_e64 v22, v22, v179, s[56:57]
	v_readlane_b32 s56, v255, 18
	v_readlane_b32 s57, v255, 19
	v_max3_f32 v10, v10, v104, v103
	v_max3_f32 v10, v10, v101, v100
	v_cndmask_b32_e64 v23, v23, v179, s[56:57]
	v_readlane_b32 s56, v255, 20
	v_readlane_b32 s57, v255, 21
	v_max3_f32 v10, v10, v99, v98
	v_max3_f32 v10, v10, v97, v95
	v_cndmask_b32_e64 v24, v24, v179, s[56:57]
	v_readlane_b32 s56, v255, 22
	v_readlane_b32 s57, v255, 23
	v_max3_f32 v10, v10, v94, v93
	v_max3_f32 v10, v10, v91, v90
	v_cndmask_b32_e64 v25, v25, v179, s[56:57]
	v_readlane_b32 s56, v255, 24
	v_readlane_b32 s57, v255, 25
	v_max3_f32 v10, v10, v86, v87
	v_max3_f32 v10, v10, v88, v89
	v_cndmask_b32_e64 v26, v26, v179, s[56:57]
	v_readlane_b32 s56, v255, 26
	v_readlane_b32 s57, v255, 27
	v_max3_f32 v10, v10, v16, v17
	v_max3_f32 v10, v10, v18, v19
	v_cndmask_b32_e64 v27, v27, v179, s[56:57]
	v_readlane_b32 s56, v255, 28
	v_readlane_b32 s57, v255, 29
	v_max3_f32 v10, v10, v20, v21
	v_max3_f32 v10, v10, v22, v23
	v_cndmask_b32_e64 v28, v28, v179, s[56:57]
	v_readlane_b32 s56, v255, 30
	v_readlane_b32 s57, v255, 31
	v_max3_f32 v10, v10, v24, v25
	v_max3_f32 v10, v10, v26, v27
	v_cndmask_b32_e64 v29, v29, v179, s[56:57]
	v_readlane_b32 s56, v255, 32
	v_readlane_b32 s57, v255, 33
	v_max3_f32 v10, v10, v28, v29
	s_waitcnt vmcnt(12)
	v_mul_f32_e32 v33, 0x3fb8aa3b, v96
	v_cndmask_b32_e64 v30, v30, v179, s[56:57]
	v_readlane_b32 s56, v255, 2
	v_readlane_b32 s57, v255, 3
	v_lshl_add_u32 v115, s93, 6, v139
	v_lshl_or_b32 v114, s12, 6, v137
	v_cndmask_b32_e64 v31, v31, v179, s[56:57]
	v_max3_f32 v10, v10, v30, v31
	ds_bpermute_b32 v32, v112, v10
	s_waitcnt lgkmcnt(0)
	v_max_f32_e32 v32, v32, v32
	v_max_f32_e32 v10, v10, v32
	v_mul_f32_e32 v10, 0x3e38aa3b, v10
	v_max_f32_e32 v10, v10, v33
	v_fma_f32 v0, v0, s18, -v10
	v_exp_f32_e32 v0, v0
	v_fma_f32 v1, v1, s18, -v10
	v_exp_f32_e32 v1, v1
	v_fma_f32 v2, v2, s18, -v10
	v_exp_f32_e32 v2, v2
	v_fma_f32 v3, v3, s18, -v10
	v_exp_f32_e32 v3, v3
	v_fma_f32 v4, v4, s18, -v10
	v_add_f32_e32 v32, 0, v0
	v_exp_f32_e32 v4, v4
	v_fma_f32 v5, v5, s18, -v10
	v_add_f32_e32 v32, v1, v32
	v_exp_f32_e32 v5, v5
	v_fma_f32 v6, v6, s18, -v10
	v_add_f32_e32 v32, v2, v32
	v_exp_f32_e32 v6, v6
	v_fma_f32 v7, v7, s18, -v10
	v_add_f32_e32 v32, v3, v32
	v_exp_f32_e32 v7, v7
	v_add_f32_e32 v32, v4, v32
	v_add_f32_e32 v32, v5, v32
	v_add_f32_e32 v32, v6, v32
	v_fma_f32 v8, v8, s18, -v10
	v_add_f32_e32 v36, v7, v32
	v_exp_f32_e32 v32, v8
	v_fma_f32 v8, v9, s18, -v10
	v_exp_f32_e32 v33, v8
	v_fma_f32 v8, v34, s18, -v10
	v_exp_f32_e32 v34, v8
	v_fma_f32 v8, v11, s18, -v10
	v_exp_f32_e32 v35, v8
	v_fma_f32 v9, v12, s18, -v10
	v_add_f32_e32 v8, v32, v36
	v_exp_f32_e32 v36, v9
	v_fma_f32 v9, v13, s18, -v10
	v_add_f32_e32 v8, v33, v8
	v_exp_f32_e32 v37, v9
	v_fma_f32 v9, v14, s18, -v10
	v_add_f32_e32 v8, v34, v8
	v_exp_f32_e32 v38, v9
	v_fma_f32 v9, v15, s18, -v10
	v_add_f32_e32 v8, v35, v8
	v_exp_f32_e32 v40, v9
	v_fma_f32 v9, v48, s18, -v10
	v_add_f32_e32 v8, v36, v8
	v_exp_f32_e32 v39, v9
	v_fma_f32 v9, v49, s18, -v10
	v_add_f32_e32 v8, v37, v8
	v_exp_f32_e32 v41, v9
	v_fma_f32 v9, v50, s18, -v10
	v_add_f32_e32 v8, v38, v8
	v_exp_f32_e32 v42, v9
	v_fma_f32 v9, v51, s18, -v10
	v_add_f32_e32 v8, v40, v8
	v_exp_f32_e32 v43, v9
	v_fma_f32 v9, v52, s18, -v10
	v_add_f32_e32 v8, v39, v8
	v_exp_f32_e32 v44, v9
	v_fma_f32 v9, v53, s18, -v10
	v_add_f32_e32 v8, v41, v8
	v_exp_f32_e32 v45, v9
	v_fma_f32 v9, v54, s18, -v10
	v_add_f32_e32 v8, v42, v8
	v_exp_f32_e32 v46, v9
	v_fma_f32 v9, v55, s18, -v10
	v_add_f32_e32 v8, v43, v8
	v_exp_f32_e32 v48, v9
	v_fma_f32 v9, v56, s18, -v10
	v_add_f32_e32 v8, v44, v8
	v_exp_f32_e32 v47, v9
	v_fma_f32 v9, v57, s18, -v10
	v_add_f32_e32 v8, v45, v8
	v_exp_f32_e32 v49, v9
	v_fma_f32 v9, v58, s18, -v10
	v_add_f32_e32 v8, v46, v8
	v_exp_f32_e32 v50, v9
	v_fma_f32 v9, v59, s18, -v10
	v_add_f32_e32 v8, v48, v8
	v_exp_f32_e32 v51, v9
	v_fma_f32 v9, v60, s18, -v10
	v_add_f32_e32 v8, v47, v8
	v_exp_f32_e32 v52, v9
	v_fma_f32 v9, v61, s18, -v10
	v_add_f32_e32 v8, v49, v8
	v_exp_f32_e32 v53, v9
	v_fma_f32 v9, v62, s18, -v10
	v_add_f32_e32 v8, v50, v8
	v_exp_f32_e32 v54, v9
	v_fma_f32 v9, v116, s18, -v10
	v_add_f32_e32 v8, v51, v8
	v_exp_f32_e32 v56, v9
	v_fma_f32 v9, v117, s18, -v10
	v_add_f32_e32 v8, v52, v8
	v_exp_f32_e32 v55, v9
	v_fma_f32 v9, v118, s18, -v10
	v_add_f32_e32 v8, v53, v8
	v_exp_f32_e32 v57, v9
	v_fma_f32 v9, v119, s18, -v10
	v_add_f32_e32 v8, v54, v8
	v_exp_f32_e32 v58, v9
	v_fma_f32 v9, v120, s18, -v10
	v_add_f32_e32 v8, v56, v8
	v_exp_f32_e32 v59, v9
	v_fma_f32 v9, v121, s18, -v10
	v_add_f32_e32 v8, v55, v8
	v_exp_f32_e32 v60, v9
	v_fma_f32 v9, v122, s18, -v10
	v_add_f32_e32 v8, v57, v8
	v_exp_f32_e32 v61, v9
	v_fma_f32 v9, v123, s18, -v10
	v_add_f32_e32 v8, v58, v8
	v_exp_f32_e32 v62, v9
	v_fma_f32 v9, v130, s18, -v10
	v_add_f32_e32 v8, v59, v8
	v_exp_f32_e32 v64, v9
	v_fma_f32 v9, v63, s18, -v10
	v_add_f32_e32 v8, v60, v8
	v_exp_f32_e32 v63, v9
	v_fma_f32 v9, v111, s18, -v10
	v_add_f32_e32 v8, v61, v8
	v_exp_f32_e32 v65, v9
	v_fma_f32 v9, v110, s18, -v10
	v_add_f32_e32 v8, v62, v8
	v_exp_f32_e32 v66, v9
	v_fma_f32 v9, v109, s18, -v10
	v_add_f32_e32 v8, v64, v8
	v_exp_f32_e32 v67, v9
	v_fma_f32 v9, v108, s18, -v10
	v_add_f32_e32 v8, v63, v8
	v_exp_f32_e32 v68, v9
	v_fma_f32 v9, v107, s18, -v10
	v_add_f32_e32 v8, v65, v8
	v_exp_f32_e32 v69, v9
	v_fma_f32 v9, v106, s18, -v10
	v_add_f32_e32 v8, v66, v8
	v_exp_f32_e32 v70, v9
	v_fma_f32 v9, v105, s18, -v10
	v_add_f32_e32 v8, v67, v8
	v_exp_f32_e32 v72, v9
	v_fma_f32 v9, v104, s18, -v10
	v_add_f32_e32 v8, v68, v8
	v_exp_f32_e32 v71, v9
	v_fma_f32 v9, v103, s18, -v10
	v_add_f32_e32 v8, v69, v8
	v_exp_f32_e32 v73, v9
	v_fma_f32 v9, v101, s18, -v10
	v_add_f32_e32 v8, v70, v8
	v_exp_f32_e32 v74, v9
	v_fma_f32 v9, v100, s18, -v10
	v_add_f32_e32 v8, v72, v8
	v_exp_f32_e32 v75, v9
	v_fma_f32 v9, v99, s18, -v10
	v_add_f32_e32 v8, v71, v8
	v_exp_f32_e32 v76, v9
	v_fma_f32 v9, v98, s18, -v10
	v_add_f32_e32 v8, v73, v8
	v_exp_f32_e32 v77, v9
	v_fma_f32 v9, v97, s18, -v10
	v_add_f32_e32 v8, v74, v8
	v_exp_f32_e32 v78, v9
	v_fma_f32 v9, v95, s18, -v10
	v_add_f32_e32 v8, v75, v8
	v_exp_f32_e32 v80, v9
	v_fma_f32 v9, v94, s18, -v10
	v_add_f32_e32 v8, v76, v8
	v_exp_f32_e32 v79, v9
	v_fma_f32 v9, v93, s18, -v10
	v_add_f32_e32 v8, v77, v8
	v_exp_f32_e32 v81, v9
	v_fma_f32 v9, v91, s18, -v10
	v_add_f32_e32 v8, v78, v8
	v_exp_f32_e32 v82, v9
	v_fma_f32 v9, v90, s18, -v10
	v_add_f32_e32 v8, v80, v8
	v_exp_f32_e32 v83, v9
	v_fma_f32 v9, v86, s18, -v10
	v_add_f32_e32 v8, v79, v8
	v_exp_f32_e32 v86, v9
	v_fma_f32 v9, v87, s18, -v10
	v_add_f32_e32 v8, v81, v8
	v_exp_f32_e32 v87, v9
	v_fma_f32 v9, v88, s18, -v10
	v_add_f32_e32 v8, v82, v8
	v_exp_f32_e32 v88, v9
	v_fma_f32 v9, v89, s18, -v10
	v_add_f32_e32 v8, v83, v8
	v_exp_f32_e32 v90, v9
	v_fma_f32 v9, v16, s18, -v10
	v_add_f32_e32 v8, v86, v8
	v_exp_f32_e32 v89, v9
	v_fma_f32 v9, v17, s18, -v10
	v_add_f32_e32 v8, v87, v8
	v_exp_f32_e32 v91, v9
	v_fma_f32 v9, v18, s18, -v10
	v_add_f32_e32 v8, v88, v8
	v_exp_f32_e32 v93, v9
	v_fma_f32 v9, v19, s18, -v10
	v_add_f32_e32 v8, v90, v8
	v_exp_f32_e32 v94, v9
	v_fma_f32 v9, v20, s18, -v10
	v_add_f32_e32 v8, v89, v8
	v_exp_f32_e32 v95, v9
	v_fma_f32 v9, v21, s18, -v10
	v_add_f32_e32 v8, v91, v8
	v_exp_f32_e32 v97, v9
	v_fma_f32 v9, v22, s18, -v10
	v_add_f32_e32 v8, v93, v8
	v_exp_f32_e32 v98, v9
	v_fma_f32 v9, v23, s18, -v10
	v_add_f32_e32 v8, v94, v8
	v_exp_f32_e32 v100, v9
	v_fma_f32 v9, v24, s18, -v10
	v_add_f32_e32 v8, v95, v8
	v_exp_f32_e32 v99, v9
	v_fma_f32 v9, v25, s18, -v10
	v_add_f32_e32 v8, v97, v8
	v_exp_f32_e32 v101, v9
	v_fma_f32 v9, v26, s18, -v10
	v_add_f32_e32 v8, v98, v8
	v_exp_f32_e32 v103, v9
	v_fma_f32 v9, v27, s18, -v10
	v_add_f32_e32 v8, v100, v8
	v_exp_f32_e32 v104, v9
	v_fma_f32 v9, v28, s18, -v10
	v_add_f32_e32 v8, v99, v8
	v_exp_f32_e32 v105, v9
	v_fma_f32 v9, v29, s18, -v10
	v_add_f32_e32 v8, v101, v8
	v_exp_f32_e32 v106, v9
	v_fma_f32 v9, v30, s18, -v10
	v_add_f32_e32 v8, v103, v8
	v_exp_f32_e32 v107, v9
	v_fma_f32 v9, v31, s18, -v10
	v_add_f32_e32 v8, v104, v8
	v_exp_f32_e32 v108, v9
	v_add_f32_e32 v8, v105, v8
	v_add_f32_e32 v8, v106, v8
	v_add_f32_e32 v8, v107, v8
	v_add_f32_e32 v8, v108, v8
	ds_bpermute_b32 v9, v112, v8
	v_fma_f32 v10, v96, s13, -v10
	v_exp_f32_e32 v10, v10
	v_cvt_pk_bf16_f32 v0, v0, v1
	v_cvt_pk_bf16_f32 v1, v2, v3
	s_waitcnt lgkmcnt(0)
	v_add_f32_e32 v8, v8, v9
	v_add_f32_e32 v96, v10, v8
	v_div_scale_f32 v8, vcc, v96, v96, 1.0
	v_rcp_f32_e32 v9, v8
	v_cvt_pk_bf16_f32 v2, v4, v5
	v_cvt_pk_bf16_f32 v3, v6, v7
	v_cvt_pk_bf16_f32 v32, v32, v33
	v_fma_f32 v10, -v8, v9, 1.0
	v_fmac_f32_e32 v9, v10, v9
	v_div_scale_f32 v10, vcc, 1.0, v96, 1.0
	v_mul_f32_e32 v11, v10, v9
	v_fma_f32 v12, -v8, v11, v10
	v_fmac_f32_e32 v11, v12, v9
	v_fma_f32 v8, -v8, v11, v10
	v_lshl_add_u32 v12, s15, 6, v139
	v_div_fmas_f32 v109, v8, v9, v11
	v_add_u32_e32 v8, v12, v157
	v_add_u32_e32 v110, 0x9000, v8
	ds_read2_b64 v[8:11], v110 offset1:2
	v_add_u32_e32 v4, v12, v158
	v_add_u32_e32 v119, 0x9000, v4
	ds_read2_b64 v[110:113], v110 offset0:4 offset1:6
	s_waitcnt lgkmcnt(1)
	v_mfma_f32_32x32x16_bf16 v[16:31], v[8:11], v[0:3], 0
	ds_read2_b64 v[4:7], v119 offset1:2
	v_cvt_pk_bf16_f32 v33, v34, v35
	v_cvt_pk_bf16_f32 v34, v36, v37
	v_cvt_pk_bf16_f32 v35, v38, v40
	v_cvt_pk_bf16_f32 v36, v39, v41
	v_cvt_pk_bf16_f32 v37, v42, v43
	v_cvt_pk_bf16_f32 v38, v44, v45
	s_waitcnt lgkmcnt(1)
	v_mfma_f32_32x32x16_bf16 v[16:31], v[110:113], v[32:35], v[16:31]
	ds_read2_b64 v[110:113], v119 offset0:4 offset1:6
	v_cvt_pk_bf16_f32 v39, v46, v48
	v_lshl_add_u32 v116, s94, 6, v139
	v_lshl_add_u32 v117, s95, 6, v139
	v_lshl_add_u32 v118, s24, 6, v139
	v_readlane_b32 s12, v254, 52
	v_readlane_b32 s13, v254, 53
	s_waitcnt lgkmcnt(1)
	v_mfma_f32_32x32x16_bf16 v[0:15], v[4:7], v[0:3], 0
	v_lshlrev_b32_e32 v130, 1, v114
	s_waitcnt lgkmcnt(0)
	v_mfma_f32_32x32x16_bf16 v[0:15], v[110:113], v[32:35], v[0:15]
	v_add_u32_e32 v32, v115, v157
	v_add_u32_e32 v40, 0x9000, v32
	ds_read2_b64 v[32:35], v40 offset1:2
	s_waitcnt lgkmcnt(0)
	v_mfma_f32_32x32x16_bf16 v[16:31], v[32:35], v[36:39], v[16:31]
	v_add_u32_e32 v32, v115, v158
	v_add_u32_e32 v41, 0x9000, v32
	ds_read2_b64 v[32:35], v41 offset1:2
	s_waitcnt lgkmcnt(0)
	v_mfma_f32_32x32x16_bf16 v[0:15], v[32:35], v[36:39], v[0:15]
	ds_read2_b64 v[32:35], v40 offset0:4 offset1:6
	v_cvt_pk_bf16_f32 v36, v47, v49
	v_cvt_pk_bf16_f32 v37, v50, v51
	v_cvt_pk_bf16_f32 v38, v52, v53
	v_cvt_pk_bf16_f32 v39, v54, v56
	s_waitcnt lgkmcnt(0)
	s_nop 0
	v_mfma_f32_32x32x16_bf16 v[16:31], v[32:35], v[36:39], v[16:31]
	ds_read2_b64 v[32:35], v41 offset0:4 offset1:6
	s_waitcnt lgkmcnt(0)
	v_mfma_f32_32x32x16_bf16 v[0:15], v[32:35], v[36:39], v[0:15]
	v_add_u32_e32 v32, v116, v157
	v_add_u32_e32 v40, 0x9000, v32
	ds_read2_b64 v[32:35], v40 offset1:2
	v_cvt_pk_bf16_f32 v36, v55, v57
	v_cvt_pk_bf16_f32 v37, v58, v59
	v_cvt_pk_bf16_f32 v38, v60, v61
	v_cvt_pk_bf16_f32 v39, v62, v64
	s_waitcnt lgkmcnt(0)
	s_nop 0
	v_mfma_f32_32x32x16_bf16 v[16:31], v[32:35], v[36:39], v[16:31]
	v_add_u32_e32 v32, v116, v158
	v_add_u32_e32 v41, 0x9000, v32
	ds_read2_b64 v[32:35], v41 offset1:2
	s_waitcnt lgkmcnt(0)
	v_mfma_f32_32x32x16_bf16 v[0:15], v[32:35], v[36:39], v[0:15]
	ds_read2_b64 v[32:35], v40 offset0:4 offset1:6
	v_cvt_pk_bf16_f32 v36, v63, v65
	v_cvt_pk_bf16_f32 v37, v66, v67
	v_cvt_pk_bf16_f32 v38, v68, v69
	v_cvt_pk_bf16_f32 v39, v70, v72
	s_waitcnt lgkmcnt(0)
	s_nop 0
	v_mfma_f32_32x32x16_bf16 v[16:31], v[32:35], v[36:39], v[16:31]
	ds_read2_b64 v[32:35], v41 offset0:4 offset1:6
	s_waitcnt lgkmcnt(0)
	v_mfma_f32_32x32x16_bf16 v[0:15], v[32:35], v[36:39], v[0:15]
	v_add_u32_e32 v32, v117, v157
	v_add_u32_e32 v40, 0x9000, v32
	ds_read2_b64 v[32:35], v40 offset1:2
	v_cvt_pk_bf16_f32 v36, v71, v73
	v_cvt_pk_bf16_f32 v37, v74, v75
	v_cvt_pk_bf16_f32 v38, v76, v77
	v_cvt_pk_bf16_f32 v39, v78, v80
	s_waitcnt lgkmcnt(0)
	s_nop 0
	v_mfma_f32_32x32x16_bf16 v[16:31], v[32:35], v[36:39], v[16:31]
	v_add_u32_e32 v32, v117, v158
	v_add_u32_e32 v41, 0x9000, v32
	ds_read2_b64 v[32:35], v41 offset1:2
	s_waitcnt lgkmcnt(0)
	v_mfma_f32_32x32x16_bf16 v[0:15], v[32:35], v[36:39], v[0:15]
	ds_read2_b64 v[32:35], v40 offset0:4 offset1:6
	v_cvt_pk_bf16_f32 v36, v79, v81
	v_cvt_pk_bf16_f32 v37, v82, v83
	v_cvt_pk_bf16_f32 v38, v86, v87
	v_cvt_pk_bf16_f32 v39, v88, v90
	s_waitcnt lgkmcnt(0)
	s_nop 0
	v_mfma_f32_32x32x16_bf16 v[16:31], v[32:35], v[36:39], v[16:31]
	ds_read2_b64 v[32:35], v41 offset0:4 offset1:6
	s_waitcnt lgkmcnt(0)
	v_mfma_f32_32x32x16_bf16 v[0:15], v[32:35], v[36:39], v[0:15]
	v_add_u32_e32 v32, v118, v157
	v_add_u32_e32 v40, 0x9000, v32
	ds_read2_b64 v[32:35], v40 offset1:2
	v_cvt_pk_bf16_f32 v36, v89, v91
	v_cvt_pk_bf16_f32 v37, v93, v94
	v_cvt_pk_bf16_f32 v38, v95, v97
	v_cvt_pk_bf16_f32 v39, v98, v100
	s_waitcnt lgkmcnt(0)
	s_nop 0
	v_mfma_f32_32x32x16_bf16 v[16:31], v[32:35], v[36:39], v[16:31]
	v_add_u32_e32 v32, v118, v158
	v_add_u32_e32 v41, 0x9000, v32
	ds_read2_b64 v[32:35], v41 offset1:2
	s_waitcnt lgkmcnt(0)
	v_mfma_f32_32x32x16_bf16 v[0:15], v[32:35], v[36:39], v[0:15]
	ds_read2_b64 v[32:35], v40 offset0:4 offset1:6
	v_cvt_pk_bf16_f32 v36, v99, v101
	v_cvt_pk_bf16_f32 v37, v103, v104
	v_cvt_pk_bf16_f32 v38, v105, v106
	v_cvt_pk_bf16_f32 v39, v107, v108
	s_waitcnt lgkmcnt(0)
	s_nop 0
	v_mfma_f32_32x32x16_bf16 v[16:31], v[32:35], v[36:39], v[16:31]
	ds_read2_b64 v[32:35], v41 offset0:4 offset1:6
	s_waitcnt lgkmcnt(0)
	v_mfma_f32_32x32x16_bf16 v[0:15], v[32:35], v[36:39], v[0:15]
	v_div_fixup_f32 v32, v109, v96, 1.0
	v_lshl_add_u64 v[34:35], s[12:13], 0, v[84:85]
	s_nop 6
	v_pk_mul_f32 v[16:17], v[16:17], v[32:33] op_sel_hi:[1,0]
	v_pk_mul_f32 v[18:19], v[18:19], v[32:33] op_sel_hi:[1,0]
	v_pk_mul_f32 v[20:21], v[20:21], v[32:33] op_sel_hi:[1,0]
	v_pk_mul_f32 v[22:23], v[22:23], v[32:33] op_sel_hi:[1,0]
	v_pk_mul_f32 v[24:25], v[24:25], v[32:33] op_sel_hi:[1,0]
	v_pk_mul_f32 v[26:27], v[26:27], v[32:33] op_sel_hi:[1,0]
	v_pk_mul_f32 v[28:29], v[28:29], v[32:33] op_sel_hi:[1,0]
	v_pk_mul_f32 v[30:31], v[30:31], v[32:33] op_sel_hi:[1,0]
	v_and_b32_e32 v152, 32, v102
	v_lshrrev_b32_e32 v152, 2, v152
	v_mov_b32_e32 v153, 0
	v_lshl_add_u64 v[200:201], v[34:35], 0, v[130:131]
	v_pk_mul_f32 v[0:1], v[0:1], v[32:33] op_sel_hi:[1,0]
	v_pk_mul_f32 v[2:3], v[2:3], v[32:33] op_sel_hi:[1,0]
	v_pk_mul_f32 v[4:5], v[4:5], v[32:33] op_sel_hi:[1,0]
	v_pk_mul_f32 v[6:7], v[6:7], v[32:33] op_sel_hi:[1,0]
	v_pk_mul_f32 v[8:9], v[8:9], v[32:33] op_sel_hi:[1,0]
	v_pk_mul_f32 v[10:11], v[10:11], v[32:33] op_sel_hi:[1,0]
	v_pk_mul_f32 v[12:13], v[12:13], v[32:33] op_sel_hi:[1,0]
	v_pk_mul_f32 v[14:15], v[14:15], v[32:33] op_sel_hi:[1,0]
	v_cvt_pk_bf16_f32 v144, v16, v17
	v_cvt_pk_bf16_f32 v145, v18, v19
	v_cvt_pk_bf16_f32 v146, v20, v21
	v_cvt_pk_bf16_f32 v147, v22, v23
	v_cvt_pk_bf16_f32 v148, v24, v25
	v_cvt_pk_bf16_f32 v149, v26, v27
	v_cvt_pk_bf16_f32 v150, v28, v29
	v_cvt_pk_bf16_f32 v151, v30, v31
	v_cvt_pk_bf16_f32 v192, v0, v1
	v_cvt_pk_bf16_f32 v193, v2, v3
	v_cvt_pk_bf16_f32 v194, v4, v5
	v_cvt_pk_bf16_f32 v195, v6, v7
	v_cvt_pk_bf16_f32 v196, v8, v9
	v_cvt_pk_bf16_f32 v197, v10, v11
	v_cvt_pk_bf16_f32 v198, v12, v13
	v_cvt_pk_bf16_f32 v199, v14, v15
	v_lshl_add_u64 v[200:201], v[200:201], 0, v[152:153]
	v_readlane_b32 s56, v254, 26
	v_readlane_b32 s57, v254, 27
	s_mov_b32 s62, 0x4c80000
	s_mov_b32 s63, 0
	s_mov_b32 s64, 0x4c7e000
	s_mov_b32 s65, 0
	s_mov_b32 s66, 0x6e80000
	s_mov_b32 s67, 0
	s_mov_b32 s68, 0x9080000
	s_mov_b32 s69, 0
	s_add_u32 s58, s56, 0x2000
	s_addc_u32 s59, s57, 0
	s_add_u32 s60, s56, 0x4000
	s_addc_u32 s61, s57, 0
	v_lshl_add_u64 v[96:97], v[200:201], 0, s[62:63]
	v_lshl_add_u64 v[98:99], v[200:201], 0, s[64:65]
	v_add_u32_e32 v100, v130, v152
	v_lshlrev_b32_e32 v100, 1, v100
	v_lshrrev_b32_e32 v32, 12, v84
	v_cmp_gt_u32_e64 s[70:71], 1, v32
	v_cmp_gt_u32_e64 s[94:95], 2, v32
	s_nop 1
	v_permlane32_swap_b32_e32 v144, v146
	v_permlane32_swap_b32_e32 v145, v147
	v_permlane32_swap_b32_e32 v148, v150
	v_permlane32_swap_b32_e32 v149, v151
	v_permlane32_swap_b32_e32 v192, v194
	v_permlane32_swap_b32_e32 v193, v195
	v_permlane32_swap_b32_e32 v196, v198
	v_permlane32_swap_b32_e32 v197, v199
	global_load_dwordx4 v[104:107], v[96:97], off offset:-4096
	global_load_dwordx4 v[0:3], v[98:99], off
	global_load_dwordx4 v[36:39], v100, s[56:57]
	global_load_dwordx4 v[40:43], v100, s[56:57] offset:16
	global_load_dwordx4 v[44:47], v100, s[58:59]
	global_load_dwordx4 v[48:51], v100, s[58:59] offset:16
	global_load_dwordx4 v[52:55], v100, s[60:61]
	global_load_dwordx4 v[56:59], v100, s[60:61] offset:16
	global_load_dwordx4 v[108:111], v[96:97], off offset:-4064
	global_load_dwordx4 v[4:7], v[98:99], off offset:32
	global_load_dwordx4 v[60:63], v100, s[56:57] offset:64
	global_load_dwordx4 v[64:67], v100, s[56:57] offset:80
	global_load_dwordx4 v[68:71], v100, s[58:59] offset:64
	global_load_dwordx4 v[72:75], v100, s[58:59] offset:80
	global_load_dwordx4 v[76:79], v100, s[60:61] offset:64
	global_load_dwordx4 v[80:83], v100, s[60:61] offset:80
	global_load_dwordx4 v[112:115], v[96:97], off offset:-4032
	global_load_dwordx4 v[8:11], v[98:99], off offset:64
	global_load_dwordx4 v[116:119], v[96:97], off offset:-4000
	global_load_dwordx4 v[12:15], v[98:99], off offset:96
	s_waitcnt vmcnt(12)
	v_cndmask_b32_e64 v104, v104, 0, s[70:71]
	v_cndmask_b32_e64 v0, v0, 0, s[94:95]
	v_cndmask_b32_e64 v105, v105, 0, s[70:71]
	v_cndmask_b32_e64 v1, v1, 0, s[94:95]
	v_cndmask_b32_e64 v106, v106, 0, s[70:71]
	v_cndmask_b32_e64 v2, v2, 0, s[94:95]
	v_cndmask_b32_e64 v107, v107, 0, s[70:71]
	v_cndmask_b32_e64 v3, v3, 0, s[94:95]
	v_lshlrev_b32_e32 v88, 16, v0
	v_and_b32_e32 v89, 0xffff0000, v0
	v_lshlrev_b32_e32 v86, 16, v104
	v_and_b32_e32 v87, 0xffff0000, v104
	v_lshlrev_b32_e32 v34, 16, v182
	v_and_b32_e32 v35, 0xffff0000, v182
	v_lshlrev_b32_e32 v32, 16, v238
	v_and_b32_e32 v33, 0xffff0000, v238
	v_lshlrev_b32_e32 v122, 16, v222
	v_and_b32_e32 v123, 0xffff0000, v222
	v_lshlrev_b32_e32 v120, 16, v144
	v_and_b32_e32 v121, 0xffff0000, v144
	v_pk_mul_f32 v[88:89], v[36:37], v[88:89]
	v_pk_fma_f32 v[88:89], v[44:45], v[86:87], v[88:89]
	v_pk_fma_f32 v[88:89], v[52:53], v[34:35], v[88:89]
	v_pk_mul_f32 v[32:33], v[32:33], v[88:89]
	v_pk_fma_f32 v[32:33], v[122:123], v[120:121], v[32:33]
	v_cvt_pk_bf16_f32 v144, v32, v33
	v_lshlrev_b32_e32 v88, 16, v1
	v_and_b32_e32 v89, 0xffff0000, v1
	v_lshlrev_b32_e32 v86, 16, v105
	v_and_b32_e32 v87, 0xffff0000, v105
	v_lshlrev_b32_e32 v34, 16, v183
	v_and_b32_e32 v35, 0xffff0000, v183
	v_lshlrev_b32_e32 v32, 16, v239
	v_and_b32_e32 v33, 0xffff0000, v239
	v_lshlrev_b32_e32 v122, 16, v223
	v_and_b32_e32 v123, 0xffff0000, v223
	v_lshlrev_b32_e32 v120, 16, v145
	v_and_b32_e32 v121, 0xffff0000, v145
	v_pk_mul_f32 v[88:89], v[38:39], v[88:89]
	v_pk_fma_f32 v[88:89], v[46:47], v[86:87], v[88:89]
	v_pk_fma_f32 v[88:89], v[54:55], v[34:35], v[88:89]
	v_pk_mul_f32 v[32:33], v[32:33], v[88:89]
	v_pk_fma_f32 v[32:33], v[122:123], v[120:121], v[32:33]
	v_cvt_pk_bf16_f32 v145, v32, v33
	v_lshlrev_b32_e32 v88, 16, v2
	v_and_b32_e32 v89, 0xffff0000, v2
	v_lshlrev_b32_e32 v86, 16, v106
	v_and_b32_e32 v87, 0xffff0000, v106
	v_lshlrev_b32_e32 v34, 16, v184
	v_and_b32_e32 v35, 0xffff0000, v184
	v_lshlrev_b32_e32 v32, 16, v240
	v_and_b32_e32 v33, 0xffff0000, v240
	v_lshlrev_b32_e32 v122, 16, v224
	v_and_b32_e32 v123, 0xffff0000, v224
	v_lshlrev_b32_e32 v120, 16, v146
	v_and_b32_e32 v121, 0xffff0000, v146
	v_pk_mul_f32 v[88:89], v[40:41], v[88:89]
	v_pk_fma_f32 v[88:89], v[48:49], v[86:87], v[88:89]
	v_pk_fma_f32 v[88:89], v[56:57], v[34:35], v[88:89]
	v_pk_mul_f32 v[32:33], v[32:33], v[88:89]
	v_pk_fma_f32 v[32:33], v[122:123], v[120:121], v[32:33]
	v_cvt_pk_bf16_f32 v146, v32, v33
	v_lshlrev_b32_e32 v88, 16, v3
	v_and_b32_e32 v89, 0xffff0000, v3
	v_lshlrev_b32_e32 v86, 16, v107
	v_and_b32_e32 v87, 0xffff0000, v107
	v_lshlrev_b32_e32 v34, 16, v185
	v_and_b32_e32 v35, 0xffff0000, v185
	v_lshlrev_b32_e32 v32, 16, v241
	v_and_b32_e32 v33, 0xffff0000, v241
	v_lshlrev_b32_e32 v122, 16, v225
	v_and_b32_e32 v123, 0xffff0000, v225
	v_lshlrev_b32_e32 v120, 16, v147
	v_and_b32_e32 v121, 0xffff0000, v147
	v_pk_mul_f32 v[88:89], v[42:43], v[88:89]
	v_pk_fma_f32 v[88:89], v[50:51], v[86:87], v[88:89]
	v_pk_fma_f32 v[88:89], v[58:59], v[34:35], v[88:89]
	v_pk_mul_f32 v[32:33], v[32:33], v[88:89]
	v_pk_fma_f32 v[32:33], v[122:123], v[120:121], v[32:33]
	v_cvt_pk_bf16_f32 v147, v32, v33
	global_store_dwordx4 v[200:201], v[144:147], off
	global_load_dwordx4 v[36:39], v100, s[56:57] offset:128
	global_load_dwordx4 v[40:43], v100, s[56:57] offset:144
	global_load_dwordx4 v[44:47], v100, s[58:59] offset:128
	global_load_dwordx4 v[48:51], v100, s[58:59] offset:144
	global_load_dwordx4 v[52:55], v100, s[60:61] offset:128
	global_load_dwordx4 v[56:59], v100, s[60:61] offset:144
	s_waitcnt vmcnt(11)
	v_cndmask_b32_e64 v108, v108, 0, s[70:71]
	v_cndmask_b32_e64 v4, v4, 0, s[94:95]
	v_cndmask_b32_e64 v109, v109, 0, s[70:71]
	v_cndmask_b32_e64 v5, v5, 0, s[94:95]
	v_cndmask_b32_e64 v110, v110, 0, s[70:71]
	v_cndmask_b32_e64 v6, v6, 0, s[94:95]
	v_cndmask_b32_e64 v111, v111, 0, s[70:71]
	v_cndmask_b32_e64 v7, v7, 0, s[94:95]
	v_lshlrev_b32_e32 v88, 16, v4
	v_and_b32_e32 v89, 0xffff0000, v4
	v_lshlrev_b32_e32 v86, 16, v108
	v_and_b32_e32 v87, 0xffff0000, v108
	v_lshlrev_b32_e32 v34, 16, v186
	v_and_b32_e32 v35, 0xffff0000, v186
	v_lshlrev_b32_e32 v32, 16, v242
	v_and_b32_e32 v33, 0xffff0000, v242
	v_lshlrev_b32_e32 v122, 16, v226
	v_and_b32_e32 v123, 0xffff0000, v226
	v_lshlrev_b32_e32 v120, 16, v148
	v_and_b32_e32 v121, 0xffff0000, v148
	v_pk_mul_f32 v[88:89], v[60:61], v[88:89]
	v_pk_fma_f32 v[88:89], v[68:69], v[86:87], v[88:89]
	v_pk_fma_f32 v[88:89], v[76:77], v[34:35], v[88:89]
	v_pk_mul_f32 v[32:33], v[32:33], v[88:89]
	v_pk_fma_f32 v[32:33], v[122:123], v[120:121], v[32:33]
	v_cvt_pk_bf16_f32 v148, v32, v33
	v_lshlrev_b32_e32 v88, 16, v5
	v_and_b32_e32 v89, 0xffff0000, v5
	v_lshlrev_b32_e32 v86, 16, v109
	v_and_b32_e32 v87, 0xffff0000, v109
	v_lshlrev_b32_e32 v34, 16, v187
	v_and_b32_e32 v35, 0xffff0000, v187
	v_lshlrev_b32_e32 v32, 16, v243
	v_and_b32_e32 v33, 0xffff0000, v243
	v_lshlrev_b32_e32 v122, 16, v227
	v_and_b32_e32 v123, 0xffff0000, v227
	v_lshlrev_b32_e32 v120, 16, v149
	v_and_b32_e32 v121, 0xffff0000, v149
	v_pk_mul_f32 v[88:89], v[62:63], v[88:89]
	v_pk_fma_f32 v[88:89], v[70:71], v[86:87], v[88:89]
	v_pk_fma_f32 v[88:89], v[78:79], v[34:35], v[88:89]
	v_pk_mul_f32 v[32:33], v[32:33], v[88:89]
	v_pk_fma_f32 v[32:33], v[122:123], v[120:121], v[32:33]
	v_cvt_pk_bf16_f32 v149, v32, v33
	v_lshlrev_b32_e32 v88, 16, v6
	v_and_b32_e32 v89, 0xffff0000, v6
	v_lshlrev_b32_e32 v86, 16, v110
	v_and_b32_e32 v87, 0xffff0000, v110
	v_lshlrev_b32_e32 v34, 16, v188
	v_and_b32_e32 v35, 0xffff0000, v188
	v_lshlrev_b32_e32 v32, 16, v244
	v_and_b32_e32 v33, 0xffff0000, v244
	v_lshlrev_b32_e32 v122, 16, v228
	v_and_b32_e32 v123, 0xffff0000, v228
	v_lshlrev_b32_e32 v120, 16, v150
	v_and_b32_e32 v121, 0xffff0000, v150
	v_pk_mul_f32 v[88:89], v[64:65], v[88:89]
	v_pk_fma_f32 v[88:89], v[72:73], v[86:87], v[88:89]
	v_pk_fma_f32 v[88:89], v[80:81], v[34:35], v[88:89]
	v_pk_mul_f32 v[32:33], v[32:33], v[88:89]
	v_pk_fma_f32 v[32:33], v[122:123], v[120:121], v[32:33]
	v_cvt_pk_bf16_f32 v150, v32, v33
	v_lshlrev_b32_e32 v88, 16, v7
	v_and_b32_e32 v89, 0xffff0000, v7
	v_lshlrev_b32_e32 v86, 16, v111
	v_and_b32_e32 v87, 0xffff0000, v111
	v_lshlrev_b32_e32 v34, 16, v189
	v_and_b32_e32 v35, 0xffff0000, v189
	v_lshlrev_b32_e32 v32, 16, v245
	v_and_b32_e32 v33, 0xffff0000, v245
	v_lshlrev_b32_e32 v122, 16, v229
	v_and_b32_e32 v123, 0xffff0000, v229
	v_lshlrev_b32_e32 v120, 16, v151
	v_and_b32_e32 v121, 0xffff0000, v151
	v_pk_mul_f32 v[88:89], v[66:67], v[88:89]
	v_pk_fma_f32 v[88:89], v[74:75], v[86:87], v[88:89]
	v_pk_fma_f32 v[88:89], v[82:83], v[34:35], v[88:89]
	v_pk_mul_f32 v[32:33], v[32:33], v[88:89]
	v_pk_fma_f32 v[32:33], v[122:123], v[120:121], v[32:33]
	v_cvt_pk_bf16_f32 v151, v32, v33
	global_store_dwordx4 v[200:201], v[148:151], off offset:32
	global_load_dwordx4 v[60:63], v100, s[56:57] offset:192
	global_load_dwordx4 v[64:67], v100, s[56:57] offset:208
	global_load_dwordx4 v[68:71], v100, s[58:59] offset:192
	global_load_dwordx4 v[72:75], v100, s[58:59] offset:208
	global_load_dwordx4 v[76:79], v100, s[60:61] offset:192
	global_load_dwordx4 v[80:83], v100, s[60:61] offset:208
	s_waitcnt vmcnt(7)
	v_cndmask_b32_e64 v112, v112, 0, s[70:71]
	v_cndmask_b32_e64 v8, v8, 0, s[94:95]
	v_cndmask_b32_e64 v113, v113, 0, s[70:71]
	v_cndmask_b32_e64 v9, v9, 0, s[94:95]
	v_cndmask_b32_e64 v114, v114, 0, s[70:71]
	v_cndmask_b32_e64 v10, v10, 0, s[94:95]
	v_cndmask_b32_e64 v115, v115, 0, s[70:71]
	v_cndmask_b32_e64 v11, v11, 0, s[94:95]
	v_lshlrev_b32_e32 v88, 16, v8
	v_and_b32_e32 v89, 0xffff0000, v8
	v_lshlrev_b32_e32 v86, 16, v112
	v_and_b32_e32 v87, 0xffff0000, v112
	v_lshlrev_b32_e32 v34, 16, v202
	v_and_b32_e32 v35, 0xffff0000, v202
	v_lshlrev_b32_e32 v32, 16, v246
	v_and_b32_e32 v33, 0xffff0000, v246
	v_lshlrev_b32_e32 v122, 16, v230
	v_and_b32_e32 v123, 0xffff0000, v230
	v_lshlrev_b32_e32 v120, 16, v192
	v_and_b32_e32 v121, 0xffff0000, v192
	v_pk_mul_f32 v[88:89], v[36:37], v[88:89]
	v_pk_fma_f32 v[88:89], v[44:45], v[86:87], v[88:89]
	v_pk_fma_f32 v[88:89], v[52:53], v[34:35], v[88:89]
	v_pk_mul_f32 v[32:33], v[32:33], v[88:89]
	v_pk_fma_f32 v[32:33], v[122:123], v[120:121], v[32:33]
	v_cvt_pk_bf16_f32 v192, v32, v33
	v_lshlrev_b32_e32 v88, 16, v9
	v_and_b32_e32 v89, 0xffff0000, v9
	v_lshlrev_b32_e32 v86, 16, v113
	v_and_b32_e32 v87, 0xffff0000, v113
	v_lshlrev_b32_e32 v34, 16, v203
	v_and_b32_e32 v35, 0xffff0000, v203
	v_lshlrev_b32_e32 v32, 16, v247
	v_and_b32_e32 v33, 0xffff0000, v247
	v_lshlrev_b32_e32 v122, 16, v231
	v_and_b32_e32 v123, 0xffff0000, v231
	v_lshlrev_b32_e32 v120, 16, v193
	v_and_b32_e32 v121, 0xffff0000, v193
	v_pk_mul_f32 v[88:89], v[38:39], v[88:89]
	v_pk_fma_f32 v[88:89], v[46:47], v[86:87], v[88:89]
	v_pk_fma_f32 v[88:89], v[54:55], v[34:35], v[88:89]
	v_pk_mul_f32 v[32:33], v[32:33], v[88:89]
	v_pk_fma_f32 v[32:33], v[122:123], v[120:121], v[32:33]
	v_cvt_pk_bf16_f32 v193, v32, v33
	v_lshlrev_b32_e32 v88, 16, v10
	v_and_b32_e32 v89, 0xffff0000, v10
	v_lshlrev_b32_e32 v86, 16, v114
	v_and_b32_e32 v87, 0xffff0000, v114
	v_lshlrev_b32_e32 v34, 16, v204
	v_and_b32_e32 v35, 0xffff0000, v204
	v_lshlrev_b32_e32 v32, 16, v248
	v_and_b32_e32 v33, 0xffff0000, v248
	v_lshlrev_b32_e32 v122, 16, v232
	v_and_b32_e32 v123, 0xffff0000, v232
	v_lshlrev_b32_e32 v120, 16, v194
	v_and_b32_e32 v121, 0xffff0000, v194
	v_pk_mul_f32 v[88:89], v[40:41], v[88:89]
	v_pk_fma_f32 v[88:89], v[48:49], v[86:87], v[88:89]
	v_pk_fma_f32 v[88:89], v[56:57], v[34:35], v[88:89]
	v_pk_mul_f32 v[32:33], v[32:33], v[88:89]
	v_pk_fma_f32 v[32:33], v[122:123], v[120:121], v[32:33]
	v_cvt_pk_bf16_f32 v194, v32, v33
	v_lshlrev_b32_e32 v88, 16, v11
	v_and_b32_e32 v89, 0xffff0000, v11
	v_lshlrev_b32_e32 v86, 16, v115
	v_and_b32_e32 v87, 0xffff0000, v115
	v_lshlrev_b32_e32 v34, 16, v205
	v_and_b32_e32 v35, 0xffff0000, v205
	v_lshlrev_b32_e32 v32, 16, v249
	v_and_b32_e32 v33, 0xffff0000, v249
	v_lshlrev_b32_e32 v122, 16, v233
	v_and_b32_e32 v123, 0xffff0000, v233
	v_lshlrev_b32_e32 v120, 16, v195
	v_and_b32_e32 v121, 0xffff0000, v195
	v_pk_mul_f32 v[88:89], v[42:43], v[88:89]
	v_pk_fma_f32 v[88:89], v[50:51], v[86:87], v[88:89]
	v_pk_fma_f32 v[88:89], v[58:59], v[34:35], v[88:89]
	v_pk_mul_f32 v[32:33], v[32:33], v[88:89]
	v_pk_fma_f32 v[32:33], v[122:123], v[120:121], v[32:33]
	v_cvt_pk_bf16_f32 v195, v32, v33
	global_store_dwordx4 v[200:201], v[192:195], off offset:64
	s_waitcnt vmcnt(1)
	v_cndmask_b32_e64 v116, v116, 0, s[70:71]
	v_cndmask_b32_e64 v12, v12, 0, s[94:95]
	v_cndmask_b32_e64 v117, v117, 0, s[70:71]
	v_cndmask_b32_e64 v13, v13, 0, s[94:95]
	v_cndmask_b32_e64 v118, v118, 0, s[70:71]
	v_cndmask_b32_e64 v14, v14, 0, s[94:95]
	v_cndmask_b32_e64 v119, v119, 0, s[70:71]
	v_cndmask_b32_e64 v15, v15, 0, s[94:95]
	v_lshlrev_b32_e32 v88, 16, v12
	v_and_b32_e32 v89, 0xffff0000, v12
	v_lshlrev_b32_e32 v86, 16, v116
	v_and_b32_e32 v87, 0xffff0000, v116
	v_lshlrev_b32_e32 v34, 16, v206
	v_and_b32_e32 v35, 0xffff0000, v206
	v_lshlrev_b32_e32 v32, 16, v250
	v_and_b32_e32 v33, 0xffff0000, v250
	v_lshlrev_b32_e32 v122, 16, v234
	v_and_b32_e32 v123, 0xffff0000, v234
	v_lshlrev_b32_e32 v120, 16, v196
	v_and_b32_e32 v121, 0xffff0000, v196
	v_pk_mul_f32 v[88:89], v[60:61], v[88:89]
	v_pk_fma_f32 v[88:89], v[68:69], v[86:87], v[88:89]
	v_pk_fma_f32 v[88:89], v[76:77], v[34:35], v[88:89]
	v_pk_mul_f32 v[32:33], v[32:33], v[88:89]
	v_pk_fma_f32 v[32:33], v[122:123], v[120:121], v[32:33]
	v_cvt_pk_bf16_f32 v196, v32, v33
	v_lshlrev_b32_e32 v88, 16, v13
	v_and_b32_e32 v89, 0xffff0000, v13
	v_lshlrev_b32_e32 v86, 16, v117
	v_and_b32_e32 v87, 0xffff0000, v117
	v_lshlrev_b32_e32 v34, 16, v207
	v_and_b32_e32 v35, 0xffff0000, v207
	v_lshlrev_b32_e32 v32, 16, v251
	v_and_b32_e32 v33, 0xffff0000, v251
	v_lshlrev_b32_e32 v122, 16, v235
	v_and_b32_e32 v123, 0xffff0000, v235
	v_lshlrev_b32_e32 v120, 16, v197
	v_and_b32_e32 v121, 0xffff0000, v197
	v_pk_mul_f32 v[88:89], v[62:63], v[88:89]
	v_pk_fma_f32 v[88:89], v[70:71], v[86:87], v[88:89]
	v_pk_fma_f32 v[88:89], v[78:79], v[34:35], v[88:89]
	v_pk_mul_f32 v[32:33], v[32:33], v[88:89]
	v_pk_fma_f32 v[32:33], v[122:123], v[120:121], v[32:33]
	v_cvt_pk_bf16_f32 v197, v32, v33
	v_lshlrev_b32_e32 v88, 16, v14
	v_and_b32_e32 v89, 0xffff0000, v14
	v_lshlrev_b32_e32 v86, 16, v118
	v_and_b32_e32 v87, 0xffff0000, v118
	v_lshlrev_b32_e32 v34, 16, v208
	v_and_b32_e32 v35, 0xffff0000, v208
	v_lshlrev_b32_e32 v32, 16, v252
	v_and_b32_e32 v33, 0xffff0000, v252
	v_lshlrev_b32_e32 v122, 16, v236
	v_and_b32_e32 v123, 0xffff0000, v236
	v_lshlrev_b32_e32 v120, 16, v198
	v_and_b32_e32 v121, 0xffff0000, v198
	v_pk_mul_f32 v[88:89], v[64:65], v[88:89]
	v_pk_fma_f32 v[88:89], v[72:73], v[86:87], v[88:89]
	v_pk_fma_f32 v[88:89], v[80:81], v[34:35], v[88:89]
	v_pk_mul_f32 v[32:33], v[32:33], v[88:89]
	v_pk_fma_f32 v[32:33], v[122:123], v[120:121], v[32:33]
	v_cvt_pk_bf16_f32 v198, v32, v33
	v_lshlrev_b32_e32 v88, 16, v15
	v_and_b32_e32 v89, 0xffff0000, v15
	v_lshlrev_b32_e32 v86, 16, v119
	v_and_b32_e32 v87, 0xffff0000, v119
	v_lshlrev_b32_e32 v34, 16, v209
	v_and_b32_e32 v35, 0xffff0000, v209
	v_lshlrev_b32_e32 v32, 16, v253
	v_and_b32_e32 v33, 0xffff0000, v253
	v_lshlrev_b32_e32 v122, 16, v237
	v_and_b32_e32 v123, 0xffff0000, v237
	v_lshlrev_b32_e32 v120, 16, v199
	v_and_b32_e32 v121, 0xffff0000, v199
	v_pk_mul_f32 v[88:89], v[66:67], v[88:89]
	v_pk_fma_f32 v[88:89], v[74:75], v[86:87], v[88:89]
	v_pk_fma_f32 v[88:89], v[82:83], v[34:35], v[88:89]
	v_pk_mul_f32 v[32:33], v[32:33], v[88:89]
	v_pk_fma_f32 v[32:33], v[122:123], v[120:121], v[32:33]
	v_cvt_pk_bf16_f32 v199, v32, v33
	global_store_dwordx4 v[200:201], v[196:199], off offset:96


	s_mov_b64 s[12:13], 0

.LBB0_808:
	v_readlane_b32 s2, v255, 36
	v_readlane_b32 s3, v254, 60
	s_add_i32 s33, s33, s2
	s_add_i32 s19, s19, s3
	s_cmpk_gt_i32 s19, 0xff
	s_cbranch_scc1 .LBB0_873
	s_branch .LBB0_709


